# v13 + stride-4 level setup slimmed: each per-lane factor from one sin/cos of the combined angle (no compare/select chains)
# speedup vs baseline: 1.0360x; 1.0003x over previous
; DI float2 twid(float r) { return float2{__builtin_amdgcn_cosf(r), -__builtin_amdgcn_sinf(r)}; }
; DI void bfly_fwd(float2 a0, float2 a1, float2 a2, float2 a3, float r, float2& o0, float2& o1, float2& o2, float2& o3) {
;   float2 t0 = {a0.x + a2.x, a0.y + a2.y}, t1 = {a0.x - a2.x, a0.y - a2.y}, t2 = {a1.x + a3.x, a1.y + a3.y}, t3 = {a1.x - a3.x, a1.y - a3.y};
;   float2 b0 = {t0.x + t2.x, t0.y + t2.y}, b2 = {t0.x - t2.x, t0.y - t2.y}, b1 = {t1.x + t3.y, t1.y - t3.x}, b3 = {t1.x - t3.y, t1.y + t3.x};
;   float2 w1 = twid(r), w2 = cmul(w1, w1), w3 = cmul(w2, w1);
;   o0 = b0; o1 = cmul(b1, w1); o2 = cmul(b2, w2); o3 = cmul(b3, w3);
; }
;   const int Q = 1 << lq; const float invM = 1.f / (float)(4 << lq);
;   for (int bb = tid; bb < NBT * (N / 4); bb += NTHR) { const int b = bb & (N / 4 - 1); float2* z = z0 + (bb / (N / 4)) * N; int j = b & (Q - 1), base = ((b >> lq) << (lq + 2)) + j; float2 o0, o1, o2, o3;
;     bfly_fwd(z[base], z[base + Q], z[base + 2 * Q], z[base + 3 * Q], (float)j * invM, o0, o1, o2, o3);
;     z[base] = o0; z[base + Q] = o1; z[base + 2 * Q] = o2; z[base + 3 * Q] = o3; }
;   __syncthreads();
.LBB0_1494:
	s_or_b64 exec, exec, s[0:1]
	s_movk_i32 s0, 0x800
	v_cmp_gt_i32_e32 vcc, s0, v10
	v_lshlrev_b32_e32 v11, 2, v10
	s_waitcnt lgkmcnt(0)
	s_barrier
	s_and_saveexec_b64 s[0:1], vcc
	s_cbranch_execz .LBB0_1497
	v_and_b32_e32 v24, 3, v10
	v_cvt_f32_ubyte0_e32 v12, v24
	v_mul_f32_e32 v13, 0x3d800000, v12
	v_sin_f32_e32 v12, v13
	v_cos_f32_e32 v14, v13
	v_lshlrev_b32_e32 v25, 2, v10
	s_mov_b64 s[10:11], 0
	v_mul_f32_e32 v13, v12, v12
	v_mul_f32_e64 v15, v14, -v12
	v_fma_f32 v16, v14, v14, -v13
	v_add_f32_e32 v18, v15, v15
	v_mul_f32_e32 v20, v12, v18
	v_mul_f32_e32 v13, v12, v16
	v_fmac_f32_e32 v20, v14, v16
	v_fma_f32 v22, v14, v18, -v13
	v_mov_b32_e32 v15, v14
	v_mov_b32_e32 v13, v12
	v_mov_b32_e32 v17, v16
	v_mov_b32_e32 v21, v20
	v_mov_b32_e32 v23, v22
	v_mov_b32_e32 v19, v18
	v_mov_b32_e32 v26, v10
	v_and_b32_e32 v244, 3, v26
	v_cvt_f32_u32_e32 v244, v244
	v_mul_f32_e32 v218, 0x3d800000, v244
	v_bfe_u32 v241, v26, 2, 2
	v_bfe_u32 v244, v26, 4, 1
	v_add_u32_e32 v241, v241, v244
	v_and_b32_e32 v241, 3, v241
	v_add_u32_e32 v244, 0, v241
	v_and_b32_e32 v244, 3, v244
	v_lshlrev_b32_e32 v236, 5, v244
	v_add_u32_e32 v244, 1, v241
	v_and_b32_e32 v244, 3, v244
	v_lshlrev_b32_e32 v237, 5, v244
	v_add_u32_e32 v244, 2, v241
	v_and_b32_e32 v244, 3, v244
	v_lshlrev_b32_e32 v238, 5, v244
	v_add_u32_e32 v244, 3, v241
	v_and_b32_e32 v244, 3, v244
	v_lshlrev_b32_e32 v239, 5, v244
	v_mul_u32_u24_e32 v243, 1, v241
	v_and_b32_e32 v243, 3, v243
	v_cvt_f32_u32_e32 v243, v243
	v_mul_f32_e32 v243, 0x3e800000, v243
	v_cos_f32_e32 v222, v243
	v_sin_f32_e32 v223, v243
	s_nop 1
	v_xor_b32_e32 v223, 0x80000000, v223
	v_mul_u32_u24_e32 v243, 2, v241
	v_and_b32_e32 v243, 3, v243
	v_cvt_f32_u32_e32 v243, v243
	v_mul_f32_e32 v243, 0x3e800000, v243
	v_cos_f32_e32 v224, v243
	v_sin_f32_e32 v225, v243
	s_nop 1
	v_xor_b32_e32 v225, 0x80000000, v225
	v_mul_u32_u24_e32 v243, 3, v241
	v_and_b32_e32 v243, 3, v243
	v_cvt_f32_u32_e32 v243, v243
	v_mul_f32_e32 v243, 0x3e800000, v243
	v_cos_f32_e32 v226, v243
	v_sin_f32_e32 v227, v243
	s_nop 1
	v_xor_b32_e32 v227, 0x80000000, v227
	v_add_u32_e32 v243, 0, v241
	v_mul_u32_u24_e32 v243, v243, v241
	v_and_b32_e32 v243, 3, v243
	v_cvt_f32_u32_e32 v243, v243
	v_add_u32_e32 v242, 0, v241
	v_and_b32_e32 v242, 3, v242
	v_cvt_f32_u32_e32 v242, v242
	v_mul_f32_e32 v242, v242, v218
	v_fmac_f32_e32 v242, 0x3e800000, v243
	v_mov_b32_e32 v243, v242
	v_cos_f32_e32 v228, v243
	v_sin_f32_e32 v229, v243
	s_nop 1
	v_xor_b32_e32 v229, 0x80000000, v229
	v_add_u32_e32 v243, 1, v241
	v_mul_u32_u24_e32 v243, v243, v241
	v_and_b32_e32 v243, 3, v243
	v_cvt_f32_u32_e32 v243, v243
	v_add_u32_e32 v242, 1, v241
	v_and_b32_e32 v242, 3, v242
	v_cvt_f32_u32_e32 v242, v242
	v_mul_f32_e32 v242, v242, v218
	v_fmac_f32_e32 v242, 0x3e800000, v243
	v_mov_b32_e32 v243, v242
	v_cos_f32_e32 v230, v243
	v_sin_f32_e32 v231, v243
	s_nop 1
	v_xor_b32_e32 v231, 0x80000000, v231
	v_add_u32_e32 v243, 2, v241
	v_mul_u32_u24_e32 v243, v243, v241
	v_and_b32_e32 v243, 3, v243
	v_cvt_f32_u32_e32 v243, v243
	v_add_u32_e32 v242, 2, v241
	v_and_b32_e32 v242, 3, v242
	v_cvt_f32_u32_e32 v242, v242
	v_mul_f32_e32 v242, v242, v218
	v_fmac_f32_e32 v242, 0x3e800000, v243
	v_mov_b32_e32 v243, v242
	v_cos_f32_e32 v232, v243
	v_sin_f32_e32 v233, v243
	s_nop 1
	v_xor_b32_e32 v233, 0x80000000, v233
	v_add_u32_e32 v243, 3, v241
	v_mul_u32_u24_e32 v243, v243, v241
	v_and_b32_e32 v243, 3, v243
	v_cvt_f32_u32_e32 v243, v243
	v_add_u32_e32 v242, 3, v241
	v_and_b32_e32 v242, 3, v242
	v_cvt_f32_u32_e32 v242, v242
	v_mul_f32_e32 v242, v242, v218
	v_fmac_f32_e32 v242, 0x3e800000, v243
	v_mov_b32_e32 v243, v242
	v_cos_f32_e32 v234, v243
	v_sin_f32_e32 v235, v243
	s_nop 1
	v_xor_b32_e32 v235, 0x80000000, v235
	s_nop 1

; DI float2 twid(float r) { return float2{__builtin_amdgcn_cosf(r), -__builtin_amdgcn_sinf(r)}; }
; DI void bfly_fwd(float2 a0, float2 a1, float2 a2, float2 a3, float r, float2& o0, float2& o1, float2& o2, float2& o3) {
;   float2 t0 = {a0.x + a2.x, a0.y + a2.y}, t1 = {a0.x - a2.x, a0.y - a2.y}, t2 = {a1.x + a3.x, a1.y + a3.y}, t3 = {a1.x - a3.x, a1.y - a3.y};
;   float2 b0 = {t0.x + t2.x, t0.y + t2.y}, b2 = {t0.x - t2.x, t0.y - t2.y}, b1 = {t1.x + t3.y, t1.y - t3.x}, b3 = {t1.x - t3.y, t1.y + t3.x};
;   float2 w1 = twid(r), w2 = cmul(w1, w1), w3 = cmul(w2, w1);
;   o0 = b0; o1 = cmul(b1, w1); o2 = cmul(b2, w2); o3 = cmul(b3, w3);
; }
;   const int Q = 1 << lq; const float invM = 1.f / (float)(4 << lq);
;   for (int bb = tid; bb < NBT * (N / 4); bb += NTHR) { const int b = bb & (N / 4 - 1); float2* z = z0 + (bb / (N / 4)) * N; int j = b & (Q - 1), base = ((b >> lq) << (lq + 2)) + j; float2 o0, o1, o2, o3;
;     bfly_fwd(z[base], z[base + Q], z[base + 2 * Q], z[base + 3 * Q], (float)j * invM, o0, o1, o2, o3);
;     z[base] = o0; z[base + Q] = o1; z[base + 2 * Q] = o2; z[base + 3 * Q] = o3; }
;   __syncthreads();
.LBB0_1522:
	s_or_b64 exec, exec, s[0:1]
	v_lshlrev_b32_e32 v11, 2, v10
	s_waitcnt lgkmcnt(0)
	s_barrier
	s_and_saveexec_b64 s[0:1], s[8:9]
	s_cbranch_execz .LBB0_1525
	v_and_b32_e32 v24, 3, v10
	v_cvt_f32_ubyte0_e32 v12, v24
	v_mul_f32_e32 v13, 0x3d800000, v12
	v_sin_f32_e32 v12, v13
	v_cos_f32_e32 v14, v13
	v_lshlrev_b32_e32 v25, 2, v10
	s_mov_b64 s[10:11], 0
	v_mul_f32_e32 v13, v12, v12
	v_mul_f32_e64 v15, v14, -v12
	v_fma_f32 v16, v14, v14, -v13
	v_add_f32_e32 v18, v15, v15
	v_mul_f32_e32 v20, v12, v18
	v_mul_f32_e32 v13, v12, v16
	v_fmac_f32_e32 v20, v14, v16
	v_fma_f32 v22, v14, v18, -v13
	v_mov_b32_e32 v15, v14
	v_mov_b32_e32 v13, v12
	v_mov_b32_e32 v17, v16
	v_mov_b32_e32 v21, v20
	v_mov_b32_e32 v23, v22
	v_mov_b32_e32 v19, v18
	v_mov_b32_e32 v26, v10
	v_and_b32_e32 v244, 3, v26
	v_cvt_f32_u32_e32 v244, v244
	v_mul_f32_e32 v218, 0x3d800000, v244
	v_bfe_u32 v241, v26, 2, 2
	v_bfe_u32 v244, v26, 4, 1
	v_add_u32_e32 v241, v241, v244
	v_and_b32_e32 v241, 3, v241
	v_add_u32_e32 v244, 0, v241
	v_and_b32_e32 v244, 3, v244
	v_lshlrev_b32_e32 v236, 5, v244
	v_add_u32_e32 v244, 1, v241
	v_and_b32_e32 v244, 3, v244
	v_lshlrev_b32_e32 v237, 5, v244
	v_add_u32_e32 v244, 2, v241
	v_and_b32_e32 v244, 3, v244
	v_lshlrev_b32_e32 v238, 5, v244
	v_add_u32_e32 v244, 3, v241
	v_and_b32_e32 v244, 3, v244
	v_lshlrev_b32_e32 v239, 5, v244
	v_mul_u32_u24_e32 v243, 1, v241
	v_and_b32_e32 v243, 3, v243
	v_cvt_f32_u32_e32 v243, v243
	v_mul_f32_e32 v243, 0x3e800000, v243
	v_cos_f32_e32 v222, v243
	v_sin_f32_e32 v223, v243
	s_nop 1
	v_xor_b32_e32 v223, 0x80000000, v223
	v_mul_u32_u24_e32 v243, 2, v241
	v_and_b32_e32 v243, 3, v243
	v_cvt_f32_u32_e32 v243, v243
	v_mul_f32_e32 v243, 0x3e800000, v243
	v_cos_f32_e32 v224, v243
	v_sin_f32_e32 v225, v243
	s_nop 1
	v_xor_b32_e32 v225, 0x80000000, v225
	v_mul_u32_u24_e32 v243, 3, v241
	v_and_b32_e32 v243, 3, v243
	v_cvt_f32_u32_e32 v243, v243
	v_mul_f32_e32 v243, 0x3e800000, v243
	v_cos_f32_e32 v226, v243
	v_sin_f32_e32 v227, v243
	s_nop 1
	v_xor_b32_e32 v227, 0x80000000, v227
	v_add_u32_e32 v243, 0, v241
	v_mul_u32_u24_e32 v243, v243, v241
	v_and_b32_e32 v243, 3, v243
	v_cvt_f32_u32_e32 v243, v243
	v_add_u32_e32 v242, 0, v241
	v_and_b32_e32 v242, 3, v242
	v_cvt_f32_u32_e32 v242, v242
	v_mul_f32_e32 v242, v242, v218
	v_fmac_f32_e32 v242, 0x3e800000, v243
	v_mov_b32_e32 v243, v242
	v_cos_f32_e32 v228, v243
	v_sin_f32_e32 v229, v243
	s_nop 1
	v_xor_b32_e32 v229, 0x80000000, v229
	v_add_u32_e32 v243, 1, v241
	v_mul_u32_u24_e32 v243, v243, v241
	v_and_b32_e32 v243, 3, v243
	v_cvt_f32_u32_e32 v243, v243
	v_add_u32_e32 v242, 1, v241
	v_and_b32_e32 v242, 3, v242
	v_cvt_f32_u32_e32 v242, v242
	v_mul_f32_e32 v242, v242, v218
	v_fmac_f32_e32 v242, 0x3e800000, v243
	v_mov_b32_e32 v243, v242
	v_cos_f32_e32 v230, v243
	v_sin_f32_e32 v231, v243
	s_nop 1
	v_xor_b32_e32 v231, 0x80000000, v231
	v_add_u32_e32 v243, 2, v241
	v_mul_u32_u24_e32 v243, v243, v241
	v_and_b32_e32 v243, 3, v243
	v_cvt_f32_u32_e32 v243, v243
	v_add_u32_e32 v242, 2, v241
	v_and_b32_e32 v242, 3, v242
	v_cvt_f32_u32_e32 v242, v242
	v_mul_f32_e32 v242, v242, v218
	v_fmac_f32_e32 v242, 0x3e800000, v243
	v_mov_b32_e32 v243, v242
	v_cos_f32_e32 v232, v243
	v_sin_f32_e32 v233, v243
	s_nop 1
	v_xor_b32_e32 v233, 0x80000000, v233
	v_add_u32_e32 v243, 3, v241
	v_mul_u32_u24_e32 v243, v243, v241
	v_and_b32_e32 v243, 3, v243
	v_cvt_f32_u32_e32 v243, v243
	v_add_u32_e32 v242, 3, v241
	v_and_b32_e32 v242, 3, v242
	v_cvt_f32_u32_e32 v242, v242
	v_mul_f32_e32 v242, v242, v218
	v_fmac_f32_e32 v242, 0x3e800000, v243
	v_mov_b32_e32 v243, v242
	v_cos_f32_e32 v234, v243
	v_sin_f32_e32 v235, v243
	s_nop 1
	v_xor_b32_e32 v235, 0x80000000, v235
	s_nop 1

; DI float2 twid(float r) { return float2{__builtin_amdgcn_cosf(r), -__builtin_amdgcn_sinf(r)}; }
; DI void bfly_fwd(float2 a0, float2 a1, float2 a2, float2 a3, float r, float2& o0, float2& o1, float2& o2, float2& o3) {
;   float2 t0 = {a0.x + a2.x, a0.y + a2.y}, t1 = {a0.x - a2.x, a0.y - a2.y}, t2 = {a1.x + a3.x, a1.y + a3.y}, t3 = {a1.x - a3.x, a1.y - a3.y};
;   float2 b0 = {t0.x + t2.x, t0.y + t2.y}, b2 = {t0.x - t2.x, t0.y - t2.y}, b1 = {t1.x + t3.y, t1.y - t3.x}, b3 = {t1.x - t3.y, t1.y + t3.x};
;   float2 w1 = twid(r), w2 = cmul(w1, w1), w3 = cmul(w2, w1);
;   o0 = b0; o1 = cmul(b1, w1); o2 = cmul(b2, w2); o3 = cmul(b3, w3);
; }
;   const int Q = 1 << lq; const float invM = 1.f / (float)(4 << lq);
;   for (int bb = tid; bb < NBT * (N / 4); bb += NTHR) { const int b = bb & (N / 4 - 1); float2* z = z0 + (bb / (N / 4)) * N; int j = b & (Q - 1), base = ((b >> lq) << (lq + 2)) + j; float2 o0, o1, o2, o3;
;     bfly_fwd(z[base], z[base + Q], z[base + 2 * Q], z[base + 3 * Q], (float)j * invM, o0, o1, o2, o3);
;     z[base] = o0; z[base + Q] = o1; z[base + 2 * Q] = o2; z[base + 3 * Q] = o3; }
;   __syncthreads();
.LBB0_1604:
	s_or_b64 exec, exec, s[0:1]
	v_and_b32_e32 v14, 3, v75
	v_cvt_f32_ubyte0_e32 v16, v14
	v_lshlrev_b32_e32 v15, 2, v75
	s_waitcnt lgkmcnt(0)
	s_barrier
	s_and_saveexec_b64 s[0:1], s[10:11]
	s_cbranch_execz .LBB0_1607
	v_mul_f32_e32 v3, 0x3d800000, v16
	v_sin_f32_e32 v2, v3
	v_cos_f32_e32 v4, v3
	v_lshlrev_b32_e32 v17, 2, v75
	s_mov_b64 s[80:81], 0
	v_mul_f32_e32 v3, v2, v2
	v_mul_f32_e64 v5, v4, -v2
	v_fma_f32 v6, v4, v4, -v3
	v_add_f32_e32 v8, v5, v5
	v_mul_f32_e32 v10, v2, v8
	v_mul_f32_e32 v3, v2, v6
	v_fmac_f32_e32 v10, v4, v6
	v_fma_f32 v12, v4, v8, -v3
	v_mov_b32_e32 v5, v4
	v_mov_b32_e32 v3, v2
	v_mov_b32_e32 v7, v6
	v_mov_b32_e32 v11, v10
	v_mov_b32_e32 v13, v12
	v_mov_b32_e32 v9, v8
	v_mov_b32_e32 v18, v75
	v_and_b32_e32 v244, 3, v18
	v_cvt_f32_u32_e32 v244, v244
	v_mul_f32_e32 v218, 0x3d800000, v244
	v_bfe_u32 v241, v18, 2, 2
	v_bfe_u32 v244, v18, 4, 1
	v_add_u32_e32 v241, v241, v244
	v_and_b32_e32 v241, 3, v241
	v_add_u32_e32 v244, 0, v241
	v_and_b32_e32 v244, 3, v244
	v_lshlrev_b32_e32 v236, 5, v244
	v_add_u32_e32 v244, 1, v241
	v_and_b32_e32 v244, 3, v244
	v_lshlrev_b32_e32 v237, 5, v244
	v_add_u32_e32 v244, 2, v241
	v_and_b32_e32 v244, 3, v244
	v_lshlrev_b32_e32 v238, 5, v244
	v_add_u32_e32 v244, 3, v241
	v_and_b32_e32 v244, 3, v244
	v_lshlrev_b32_e32 v239, 5, v244
	v_mul_u32_u24_e32 v243, 1, v241
	v_and_b32_e32 v243, 3, v243
	v_cvt_f32_u32_e32 v243, v243
	v_mul_f32_e32 v243, 0x3e800000, v243
	v_cos_f32_e32 v222, v243
	v_sin_f32_e32 v223, v243
	s_nop 1
	v_xor_b32_e32 v223, 0x80000000, v223
	v_mul_u32_u24_e32 v243, 2, v241
	v_and_b32_e32 v243, 3, v243
	v_cvt_f32_u32_e32 v243, v243
	v_mul_f32_e32 v243, 0x3e800000, v243
	v_cos_f32_e32 v224, v243
	v_sin_f32_e32 v225, v243
	s_nop 1
	v_xor_b32_e32 v225, 0x80000000, v225
	v_mul_u32_u24_e32 v243, 3, v241
	v_and_b32_e32 v243, 3, v243
	v_cvt_f32_u32_e32 v243, v243
	v_mul_f32_e32 v243, 0x3e800000, v243
	v_cos_f32_e32 v226, v243
	v_sin_f32_e32 v227, v243
	s_nop 1
	v_xor_b32_e32 v227, 0x80000000, v227
	v_add_u32_e32 v243, 0, v241
	v_mul_u32_u24_e32 v243, v243, v241
	v_and_b32_e32 v243, 3, v243
	v_cvt_f32_u32_e32 v243, v243
	v_add_u32_e32 v242, 0, v241
	v_and_b32_e32 v242, 3, v242
	v_cvt_f32_u32_e32 v242, v242
	v_mul_f32_e32 v242, v242, v218
	v_fmac_f32_e32 v242, 0x3e800000, v243
	v_mov_b32_e32 v243, v242
	v_cos_f32_e32 v228, v243
	v_sin_f32_e32 v229, v243
	s_nop 1
	v_xor_b32_e32 v229, 0x80000000, v229
	v_add_u32_e32 v243, 1, v241
	v_mul_u32_u24_e32 v243, v243, v241
	v_and_b32_e32 v243, 3, v243
	v_cvt_f32_u32_e32 v243, v243
	v_add_u32_e32 v242, 1, v241
	v_and_b32_e32 v242, 3, v242
	v_cvt_f32_u32_e32 v242, v242
	v_mul_f32_e32 v242, v242, v218
	v_fmac_f32_e32 v242, 0x3e800000, v243
	v_mov_b32_e32 v243, v242
	v_cos_f32_e32 v230, v243
	v_sin_f32_e32 v231, v243
	s_nop 1
	v_xor_b32_e32 v231, 0x80000000, v231
	v_add_u32_e32 v243, 2, v241
	v_mul_u32_u24_e32 v243, v243, v241
	v_and_b32_e32 v243, 3, v243
	v_cvt_f32_u32_e32 v243, v243
	v_add_u32_e32 v242, 2, v241
	v_and_b32_e32 v242, 3, v242
	v_cvt_f32_u32_e32 v242, v242
	v_mul_f32_e32 v242, v242, v218
	v_fmac_f32_e32 v242, 0x3e800000, v243
	v_mov_b32_e32 v243, v242
	v_cos_f32_e32 v232, v243
	v_sin_f32_e32 v233, v243
	s_nop 1
	v_xor_b32_e32 v233, 0x80000000, v233
	v_add_u32_e32 v243, 3, v241
	v_mul_u32_u24_e32 v243, v243, v241
	v_and_b32_e32 v243, 3, v243
	v_cvt_f32_u32_e32 v243, v243
	v_add_u32_e32 v242, 3, v241
	v_and_b32_e32 v242, 3, v242
	v_cvt_f32_u32_e32 v242, v242
	v_mul_f32_e32 v242, v242, v218
	v_fmac_f32_e32 v242, 0x3e800000, v243
	v_mov_b32_e32 v243, v242
	v_cos_f32_e32 v234, v243
	v_sin_f32_e32 v235, v243
	s_nop 1
	v_xor_b32_e32 v235, 0x80000000, v235
	s_nop 1

; DI float2 twid(float r) { return float2{__builtin_amdgcn_cosf(r), -__builtin_amdgcn_sinf(r)}; }
; DI void bfly_inv(float2 s0, float2 s1, float2 s2, float2 s3, float r, float2& o0, float2& o1, float2& o2, float2& o3) {
;   float2 w1 = twid(r), w2 = cmul(w1, w1), w3 = cmul(w2, w1);
;   float2 c0 = s0, c1 = cmulc(s1, w1), c2 = cmulc(s2, w2), c3 = cmulc(s3, w3);
;   const int Q = 1 << lq; const float invM = 1.f / (float)(4 << lq);
;   for (int bb = tid; bb < NBT * (N / 4); bb += NTHR) { const int b = bb & (N / 4 - 1); float2* z = z0 + (bb / (N / 4)) * N; int j = b & (Q - 1), base = ((b >> lq) << (lq + 2)) + j; float2 o0, o1, o2, o3;
;     bfly_inv(z[base], z[base + Q], z[base + 2 * Q], z[base + 3 * Q], (float)j * invM, o0, o1, o2, o3);
;     z[base] = o0; z[base + Q] = o1; z[base + 2 * Q] = o2; z[base + 3 * Q] = o3; }
;   __syncthreads();
.LBB0_1613:
	s_or_b64 exec, exec, s[0:1]
	s_waitcnt lgkmcnt(0)
	s_barrier
	s_and_saveexec_b64 s[0:1], s[10:11]
	s_cbranch_execz .LBB0_1616
	v_mul_f32_e32 v2, 0x3d800000, v16
	v_sin_f32_e32 v3, v2
	v_cos_f32_e32 v5, v2
	s_mov_b64 s[80:81], 0
	v_mov_b32_e32 v16, v75
	v_mul_f32_e32 v2, v3, v3
	v_mul_f32_e64 v4, v5, -v3
	v_fma_f32 v6, v5, v5, -v2
	v_add_f32_e32 v8, v4, v4
	v_mul_f32_e32 v2, v3, v8
	v_mul_f32_e32 v4, v3, v6
	v_fmac_f32_e32 v2, v5, v6
	v_fma_f32 v4, v5, v8, -v4
	v_mov_b32_e32 v7, v6
	v_pk_mov_b32 v[10:11], v[4:5], v[2:3] op_sel:[1,0]
	v_pk_mov_b32 v[12:13], v[2:3], v[4:5] op_sel:[1,0]
	v_mov_b32_e32 v9, v8
	v_and_b32_e32 v248, 3, v16
	v_cvt_f32_u32_e32 v248, v248
	v_mul_f32_e32 v220, 0x3d800000, v248
	v_bfe_u32 v245, v16, 2, 2
	v_bfe_u32 v248, v16, 4, 1
	v_add_u32_e32 v245, v245, v248
	v_and_b32_e32 v245, 3, v245
	v_add_u32_e32 v248, 0, v245
	v_and_b32_e32 v248, 3, v248
	v_lshlrev_b32_e32 v241, 5, v248
	v_add_u32_e32 v248, 1, v245
	v_and_b32_e32 v248, 3, v248
	v_lshlrev_b32_e32 v242, 5, v248
	v_add_u32_e32 v248, 2, v245
	v_and_b32_e32 v248, 3, v248
	v_lshlrev_b32_e32 v243, 5, v248
	v_add_u32_e32 v248, 3, v245
	v_and_b32_e32 v248, 3, v248
	v_lshlrev_b32_e32 v244, 5, v248
	v_mul_u32_u24_e32 v247, 0, v245
	v_and_b32_e32 v247, 3, v247
	v_cvt_f32_u32_e32 v247, v247
	v_add_u32_e32 v246, 0, v245
	v_and_b32_e32 v246, 3, v246
	v_cvt_f32_u32_e32 v246, v246
	v_mul_f32_e32 v246, v246, v220
	v_fmac_f32_e32 v246, 0x3e800000, v247
	v_mov_b32_e32 v247, v246
	v_cos_f32_e32 v224, v247
	v_sin_f32_e32 v225, v247
	v_mul_u32_u24_e32 v247, 1, v245
	v_and_b32_e32 v247, 3, v247
	v_cvt_f32_u32_e32 v247, v247
	v_add_u32_e32 v246, 1, v245
	v_and_b32_e32 v246, 3, v246
	v_cvt_f32_u32_e32 v246, v246
	v_mul_f32_e32 v246, v246, v220
	v_fmac_f32_e32 v246, 0x3e800000, v247
	v_mov_b32_e32 v247, v246
	v_cos_f32_e32 v226, v247
	v_sin_f32_e32 v227, v247
	v_mul_u32_u24_e32 v247, 2, v245
	v_and_b32_e32 v247, 3, v247
	v_cvt_f32_u32_e32 v247, v247
	v_add_u32_e32 v246, 2, v245
	v_and_b32_e32 v246, 3, v246
	v_cvt_f32_u32_e32 v246, v246
	v_mul_f32_e32 v246, v246, v220
	v_fmac_f32_e32 v246, 0x3e800000, v247
	v_mov_b32_e32 v247, v246
	v_cos_f32_e32 v228, v247
	v_sin_f32_e32 v229, v247
	v_mul_u32_u24_e32 v247, 3, v245
	v_and_b32_e32 v247, 3, v247
	v_cvt_f32_u32_e32 v247, v247
	v_add_u32_e32 v246, 3, v245
	v_and_b32_e32 v246, 3, v246
	v_cvt_f32_u32_e32 v246, v246
	v_mul_f32_e32 v246, v246, v220
	v_fmac_f32_e32 v246, 0x3e800000, v247
	v_mov_b32_e32 v247, v246
	v_cos_f32_e32 v230, v247
	v_sin_f32_e32 v231, v247
	v_add_u32_e32 v247, 0, v245
	v_mul_u32_u24_e32 v247, v247, v245
	v_and_b32_e32 v247, 3, v247
	v_cvt_f32_u32_e32 v247, v247
	v_mul_f32_e32 v247, 0x3e800000, v247
	v_cos_f32_e32 v232, v247
	v_sin_f32_e32 v233, v247
	v_add_u32_e32 v247, 1, v245
	v_mul_u32_u24_e32 v247, v247, v245
	v_and_b32_e32 v247, 3, v247
	v_cvt_f32_u32_e32 v247, v247
	v_mul_f32_e32 v247, 0x3e800000, v247
	v_cos_f32_e32 v234, v247
	v_sin_f32_e32 v235, v247
	v_add_u32_e32 v247, 2, v245
	v_mul_u32_u24_e32 v247, v247, v245
	v_and_b32_e32 v247, 3, v247
	v_cvt_f32_u32_e32 v247, v247
	v_mul_f32_e32 v247, 0x3e800000, v247
	v_cos_f32_e32 v236, v247
	v_sin_f32_e32 v237, v247
	v_add_u32_e32 v247, 3, v245
	v_mul_u32_u24_e32 v247, v247, v245
	v_and_b32_e32 v247, 3, v247
	v_cvt_f32_u32_e32 v247, v247
	v_mul_f32_e32 v247, 0x3e800000, v247
	v_cos_f32_e32 v238, v247
	v_sin_f32_e32 v239, v247
	s_nop 1

; DI float2 twid(float r) { return float2{__builtin_amdgcn_cosf(r), -__builtin_amdgcn_sinf(r)}; }
; DI void bfly_fwd(float2 a0, float2 a1, float2 a2, float2 a3, float r, float2& o0, float2& o1, float2& o2, float2& o3) {
;   float2 t0 = {a0.x + a2.x, a0.y + a2.y}, t1 = {a0.x - a2.x, a0.y - a2.y}, t2 = {a1.x + a3.x, a1.y + a3.y}, t3 = {a1.x - a3.x, a1.y - a3.y};
;   float2 b0 = {t0.x + t2.x, t0.y + t2.y}, b2 = {t0.x - t2.x, t0.y - t2.y}, b1 = {t1.x + t3.y, t1.y - t3.x}, b3 = {t1.x - t3.y, t1.y + t3.x};
;   float2 w1 = twid(r), w2 = cmul(w1, w1), w3 = cmul(w2, w1);
;   o0 = b0; o1 = cmul(b1, w1); o2 = cmul(b2, w2); o3 = cmul(b3, w3);
; }
;   const int Q = 1 << lq; const float invM = 1.f / (float)(4 << lq);
;   for (int bb = tid; bb < NBT * (N / 4); bb += NTHR) { const int b = bb & (N / 4 - 1); float2* z = z0 + (bb / (N / 4)) * N; int j = b & (Q - 1), base = ((b >> lq) << (lq + 2)) + j; float2 o0, o1, o2, o3;
;     bfly_fwd(z[base], z[base + Q], z[base + 2 * Q], z[base + 3 * Q], (float)j * invM, o0, o1, o2, o3);
;     z[base] = o0; z[base + Q] = o1; z[base + 2 * Q] = o2; z[base + 3 * Q] = o3; }
;   __syncthreads();
.LBB0_1636:
	s_or_b64 exec, exec, s[0:1]
	s_movk_i32 s0, 0x1000
	v_and_b32_e32 v16, 3, v76
	v_cmp_gt_i32_e64 s[12:13], s0, v76
	v_cvt_f32_ubyte0_e32 v18, v16
	v_lshlrev_b32_e32 v17, 2, v76
	s_waitcnt lgkmcnt(0)
	s_barrier
	s_and_saveexec_b64 s[0:1], s[12:13]
	s_cbranch_execz .LBB0_1639
	v_mul_f32_e32 v5, 0x3d800000, v18
	v_sin_f32_e32 v4, v5
	v_cos_f32_e32 v6, v5
	v_lshlrev_b32_e32 v19, 2, v76
	s_mov_b64 s[80:81], 0
	v_mul_f32_e32 v5, v4, v4
	v_mul_f32_e64 v7, v6, -v4
	v_fma_f32 v8, v6, v6, -v5
	v_add_f32_e32 v10, v7, v7
	v_mul_f32_e32 v12, v4, v10
	v_mul_f32_e32 v5, v4, v8
	v_fmac_f32_e32 v12, v6, v8
	v_fma_f32 v14, v6, v10, -v5
	v_mov_b32_e32 v7, v6
	v_mov_b32_e32 v5, v4
	v_mov_b32_e32 v9, v8
	v_mov_b32_e32 v13, v12
	v_mov_b32_e32 v15, v14
	v_mov_b32_e32 v11, v10
	v_mov_b32_e32 v20, v76
	v_and_b32_e32 v244, 3, v20
	v_cvt_f32_u32_e32 v244, v244
	v_mul_f32_e32 v218, 0x3d800000, v244
	v_bfe_u32 v241, v20, 2, 2
	v_bfe_u32 v244, v20, 4, 1
	v_add_u32_e32 v241, v241, v244
	v_and_b32_e32 v241, 3, v241
	v_add_u32_e32 v244, 0, v241
	v_and_b32_e32 v244, 3, v244
	v_lshlrev_b32_e32 v236, 5, v244
	v_add_u32_e32 v244, 1, v241
	v_and_b32_e32 v244, 3, v244
	v_lshlrev_b32_e32 v237, 5, v244
	v_add_u32_e32 v244, 2, v241
	v_and_b32_e32 v244, 3, v244
	v_lshlrev_b32_e32 v238, 5, v244
	v_add_u32_e32 v244, 3, v241
	v_and_b32_e32 v244, 3, v244
	v_lshlrev_b32_e32 v239, 5, v244
	v_mul_u32_u24_e32 v243, 1, v241
	v_and_b32_e32 v243, 3, v243
	v_cvt_f32_u32_e32 v243, v243
	v_mul_f32_e32 v243, 0x3e800000, v243
	v_cos_f32_e32 v222, v243
	v_sin_f32_e32 v223, v243
	s_nop 1
	v_xor_b32_e32 v223, 0x80000000, v223
	v_mul_u32_u24_e32 v243, 2, v241
	v_and_b32_e32 v243, 3, v243
	v_cvt_f32_u32_e32 v243, v243
	v_mul_f32_e32 v243, 0x3e800000, v243
	v_cos_f32_e32 v224, v243
	v_sin_f32_e32 v225, v243
	s_nop 1
	v_xor_b32_e32 v225, 0x80000000, v225
	v_mul_u32_u24_e32 v243, 3, v241
	v_and_b32_e32 v243, 3, v243
	v_cvt_f32_u32_e32 v243, v243
	v_mul_f32_e32 v243, 0x3e800000, v243
	v_cos_f32_e32 v226, v243
	v_sin_f32_e32 v227, v243
	s_nop 1
	v_xor_b32_e32 v227, 0x80000000, v227
	v_add_u32_e32 v243, 0, v241
	v_mul_u32_u24_e32 v243, v243, v241
	v_and_b32_e32 v243, 3, v243
	v_cvt_f32_u32_e32 v243, v243
	v_add_u32_e32 v242, 0, v241
	v_and_b32_e32 v242, 3, v242
	v_cvt_f32_u32_e32 v242, v242
	v_mul_f32_e32 v242, v242, v218
	v_fmac_f32_e32 v242, 0x3e800000, v243
	v_mov_b32_e32 v243, v242
	v_cos_f32_e32 v228, v243
	v_sin_f32_e32 v229, v243
	s_nop 1
	v_xor_b32_e32 v229, 0x80000000, v229
	v_add_u32_e32 v243, 1, v241
	v_mul_u32_u24_e32 v243, v243, v241
	v_and_b32_e32 v243, 3, v243
	v_cvt_f32_u32_e32 v243, v243
	v_add_u32_e32 v242, 1, v241
	v_and_b32_e32 v242, 3, v242
	v_cvt_f32_u32_e32 v242, v242
	v_mul_f32_e32 v242, v242, v218
	v_fmac_f32_e32 v242, 0x3e800000, v243
	v_mov_b32_e32 v243, v242
	v_cos_f32_e32 v230, v243
	v_sin_f32_e32 v231, v243
	s_nop 1
	v_xor_b32_e32 v231, 0x80000000, v231
	v_add_u32_e32 v243, 2, v241
	v_mul_u32_u24_e32 v243, v243, v241
	v_and_b32_e32 v243, 3, v243
	v_cvt_f32_u32_e32 v243, v243
	v_add_u32_e32 v242, 2, v241
	v_and_b32_e32 v242, 3, v242
	v_cvt_f32_u32_e32 v242, v242
	v_mul_f32_e32 v242, v242, v218
	v_fmac_f32_e32 v242, 0x3e800000, v243
	v_mov_b32_e32 v243, v242
	v_cos_f32_e32 v232, v243
	v_sin_f32_e32 v233, v243
	s_nop 1
	v_xor_b32_e32 v233, 0x80000000, v233
	v_add_u32_e32 v243, 3, v241
	v_mul_u32_u24_e32 v243, v243, v241
	v_and_b32_e32 v243, 3, v243
	v_cvt_f32_u32_e32 v243, v243
	v_add_u32_e32 v242, 3, v241
	v_and_b32_e32 v242, 3, v242
	v_cvt_f32_u32_e32 v242, v242
	v_mul_f32_e32 v242, v242, v218
	v_fmac_f32_e32 v242, 0x3e800000, v243
	v_mov_b32_e32 v243, v242
	v_cos_f32_e32 v234, v243
	v_sin_f32_e32 v235, v243
	s_nop 1
	v_xor_b32_e32 v235, 0x80000000, v235
	s_nop 1

; DI float2 twid(float r) { return float2{__builtin_amdgcn_cosf(r), -__builtin_amdgcn_sinf(r)}; }
; DI void bfly_inv(float2 s0, float2 s1, float2 s2, float2 s3, float r, float2& o0, float2& o1, float2& o2, float2& o3) {
;   float2 w1 = twid(r), w2 = cmul(w1, w1), w3 = cmul(w2, w1);
;   float2 c0 = s0, c1 = cmulc(s1, w1), c2 = cmulc(s2, w2), c3 = cmulc(s3, w3);
;   const int Q = 1 << lq; const float invM = 1.f / (float)(4 << lq);
;   for (int bb = tid; bb < NBT * (N / 4); bb += NTHR) { const int b = bb & (N / 4 - 1); float2* z = z0 + (bb / (N / 4)) * N; int j = b & (Q - 1), base = ((b >> lq) << (lq + 2)) + j; float2 o0, o1, o2, o3;
;     bfly_inv(z[base], z[base + Q], z[base + 2 * Q], z[base + 3 * Q], (float)j * invM, o0, o1, o2, o3);
;     z[base] = o0; z[base + Q] = o1; z[base + 2 * Q] = o2; z[base + 3 * Q] = o3; }
;   __syncthreads();
.LBB0_1645:
	s_or_b64 exec, exec, s[0:1]
	s_waitcnt lgkmcnt(0)
	s_barrier
	s_and_saveexec_b64 s[0:1], s[12:13]
	s_cbranch_execz .LBB0_1648
	v_mul_f32_e32 v4, 0x3d800000, v18
	v_sin_f32_e32 v5, v4
	v_cos_f32_e32 v7, v4
	s_mov_b64 s[14:15], 0
	v_mov_b32_e32 v18, v76
	v_mul_f32_e32 v4, v5, v5
	v_mul_f32_e64 v6, v7, -v5
	v_fma_f32 v8, v7, v7, -v4
	v_add_f32_e32 v10, v6, v6
	v_mul_f32_e32 v4, v5, v10
	v_mul_f32_e32 v6, v5, v8
	v_fmac_f32_e32 v4, v7, v8
	v_fma_f32 v6, v7, v10, -v6
	v_mov_b32_e32 v9, v8
	v_pk_mov_b32 v[12:13], v[6:7], v[4:5] op_sel:[1,0]
	v_pk_mov_b32 v[14:15], v[4:5], v[6:7] op_sel:[1,0]
	v_mov_b32_e32 v11, v10
	v_and_b32_e32 v248, 3, v18
	v_cvt_f32_u32_e32 v248, v248
	v_mul_f32_e32 v220, 0x3d800000, v248
	v_bfe_u32 v245, v18, 2, 2
	v_bfe_u32 v248, v18, 4, 1
	v_add_u32_e32 v245, v245, v248
	v_and_b32_e32 v245, 3, v245
	v_add_u32_e32 v248, 0, v245
	v_and_b32_e32 v248, 3, v248
	v_lshlrev_b32_e32 v241, 5, v248
	v_add_u32_e32 v248, 1, v245
	v_and_b32_e32 v248, 3, v248
	v_lshlrev_b32_e32 v242, 5, v248
	v_add_u32_e32 v248, 2, v245
	v_and_b32_e32 v248, 3, v248
	v_lshlrev_b32_e32 v243, 5, v248
	v_add_u32_e32 v248, 3, v245
	v_and_b32_e32 v248, 3, v248
	v_lshlrev_b32_e32 v244, 5, v248
	v_mul_u32_u24_e32 v247, 0, v245
	v_and_b32_e32 v247, 3, v247
	v_cvt_f32_u32_e32 v247, v247
	v_add_u32_e32 v246, 0, v245
	v_and_b32_e32 v246, 3, v246
	v_cvt_f32_u32_e32 v246, v246
	v_mul_f32_e32 v246, v246, v220
	v_fmac_f32_e32 v246, 0x3e800000, v247
	v_mov_b32_e32 v247, v246
	v_cos_f32_e32 v224, v247
	v_sin_f32_e32 v225, v247
	v_mul_u32_u24_e32 v247, 1, v245
	v_and_b32_e32 v247, 3, v247
	v_cvt_f32_u32_e32 v247, v247
	v_add_u32_e32 v246, 1, v245
	v_and_b32_e32 v246, 3, v246
	v_cvt_f32_u32_e32 v246, v246
	v_mul_f32_e32 v246, v246, v220
	v_fmac_f32_e32 v246, 0x3e800000, v247
	v_mov_b32_e32 v247, v246
	v_cos_f32_e32 v226, v247
	v_sin_f32_e32 v227, v247
	v_mul_u32_u24_e32 v247, 2, v245
	v_and_b32_e32 v247, 3, v247
	v_cvt_f32_u32_e32 v247, v247
	v_add_u32_e32 v246, 2, v245
	v_and_b32_e32 v246, 3, v246
	v_cvt_f32_u32_e32 v246, v246
	v_mul_f32_e32 v246, v246, v220
	v_fmac_f32_e32 v246, 0x3e800000, v247
	v_mov_b32_e32 v247, v246
	v_cos_f32_e32 v228, v247
	v_sin_f32_e32 v229, v247
	v_mul_u32_u24_e32 v247, 3, v245
	v_and_b32_e32 v247, 3, v247
	v_cvt_f32_u32_e32 v247, v247
	v_add_u32_e32 v246, 3, v245
	v_and_b32_e32 v246, 3, v246
	v_cvt_f32_u32_e32 v246, v246
	v_mul_f32_e32 v246, v246, v220
	v_fmac_f32_e32 v246, 0x3e800000, v247
	v_mov_b32_e32 v247, v246
	v_cos_f32_e32 v230, v247
	v_sin_f32_e32 v231, v247
	v_add_u32_e32 v247, 0, v245
	v_mul_u32_u24_e32 v247, v247, v245
	v_and_b32_e32 v247, 3, v247
	v_cvt_f32_u32_e32 v247, v247
	v_mul_f32_e32 v247, 0x3e800000, v247
	v_cos_f32_e32 v232, v247
	v_sin_f32_e32 v233, v247
	v_add_u32_e32 v247, 1, v245
	v_mul_u32_u24_e32 v247, v247, v245
	v_and_b32_e32 v247, 3, v247
	v_cvt_f32_u32_e32 v247, v247
	v_mul_f32_e32 v247, 0x3e800000, v247
	v_cos_f32_e32 v234, v247
	v_sin_f32_e32 v235, v247
	v_add_u32_e32 v247, 2, v245
	v_mul_u32_u24_e32 v247, v247, v245
	v_and_b32_e32 v247, 3, v247
	v_cvt_f32_u32_e32 v247, v247
	v_mul_f32_e32 v247, 0x3e800000, v247
	v_cos_f32_e32 v236, v247
	v_sin_f32_e32 v237, v247
	v_add_u32_e32 v247, 3, v245
	v_mul_u32_u24_e32 v247, v247, v245
	v_and_b32_e32 v247, 3, v247
	v_cvt_f32_u32_e32 v247, v247
	v_mul_f32_e32 v247, 0x3e800000, v247
	v_cos_f32_e32 v238, v247
	v_sin_f32_e32 v239, v247
	s_nop 1
